# bundle23 + scaled weight-transpose path (P0 W_in, P4 FFN2 W_gate_up copies): the 16 row-gain loads are issued together instead of 8 serialized pairs
# speedup vs baseline: 1.0118x; 1.0027x over previous
.LBB0_60:
	s_or_b64 exec, exec, s[10:11]
	v_cndmask_b32_e64 v1, 0, 1, s[0:1]
	v_cmp_ne_u32_e64 s[2:3], 1, v1
	s_andn2_b64 vcc, exec, s[0:1]
	v_lshlrev_b32_e32 v82, 2, v130
	s_cbranch_vccnz .LBB0_198
	global_load_dword v130, v82, s[78:79]
	global_load_dword v66, v82, s[78:79] offset:16
	global_load_dword v200, v82, s[78:79] offset:32
	global_load_dword v202, v82, s[78:79] offset:48
	global_load_dword v204, v82, s[78:79] offset:64
	global_load_dword v206, v82, s[78:79] offset:80
	global_load_dword v208, v82, s[78:79] offset:96
	global_load_dword v210, v82, s[78:79] offset:112
	global_load_dword v212, v82, s[78:79] offset:128
	global_load_dword v214, v82, s[78:79] offset:144
	global_load_dword v216, v82, s[78:79] offset:160
	global_load_dword v218, v82, s[78:79] offset:176
	global_load_dword v220, v82, s[78:79] offset:192
	global_load_dword v222, v82, s[78:79] offset:208
	global_load_dword v224, v82, s[78:79] offset:224
	global_load_dword v226, v82, s[78:79] offset:240
	s_waitcnt vmcnt(15)
	v_pk_mul_f32 v[132:133], v[6:7], v[130:131] op_sel_hi:[1,0]
	v_pk_mul_f32 v[130:131], v[8:9], v[130:131] op_sel_hi:[1,0]
	ds_write2_b32 v86, v132, v133 offset1:1
	ds_write2_b32 v86, v130, v131 offset0:2 offset1:3
	s_cbranch_execnz .LBB0_63

.LBB0_63:
	s_waitcnt vmcnt(14)
	v_pk_mul_f32 v[2:3], v[2:3], v[66:67] op_sel_hi:[1,0]
	ds_write2_b32 v96, v2, v3 offset1:1
	v_pk_mul_f32 v[2:3], v[4:5], v[66:67] op_sel_hi:[1,0]
	s_and_b64 vcc, exec, s[2:3]
	ds_write2_b32 v97, v2, v3 offset1:1
	s_cbranch_vccnz .LBB0_199
	s_waitcnt vmcnt(13)
	v_pk_mul_f32 v[6:7], v[14:15], v[200:201] op_sel_hi:[1,0]
	v_pk_mul_f32 v[4:5], v[16:17], v[200:201] op_sel_hi:[1,0]
	ds_write2_b32 v98, v6, v7 offset1:1
	ds_write2_b32 v99, v4, v5 offset1:1
	s_cbranch_execnz .LBB0_66
.LBB0_65:
	s_waitcnt vmcnt(0)
	v_mov_b32_e32 v202, 1.0
	ds_write2_b32 v98, v14, v15 offset1:1
	ds_write2_b32 v99, v16, v17 offset1:1
.LBB0_66:
	s_waitcnt vmcnt(12)
	v_pk_mul_f32 v[4:5], v[10:11], v[202:203] op_sel_hi:[1,0]
	v_pk_mul_f32 v[2:3], v[12:13], v[202:203] op_sel_hi:[1,0]
	s_and_b64 vcc, exec, s[2:3]
	ds_write2_b32 v100, v4, v5 offset1:1
	ds_write2_b32 v101, v2, v3 offset1:1
	s_cbranch_vccnz .LBB0_200
	s_waitcnt vmcnt(11)
	v_pk_mul_f32 v[6:7], v[22:23], v[204:205] op_sel_hi:[1,0]
	v_pk_mul_f32 v[4:5], v[24:25], v[204:205] op_sel_hi:[1,0]
	ds_write2_b32 v102, v6, v7 offset1:1
	ds_write2_b32 v103, v4, v5 offset1:1
	s_cbranch_execnz .LBB0_69
.LBB0_68:
	s_waitcnt vmcnt(0)
	v_mov_b32_e32 v206, 1.0
	ds_write2_b32 v102, v22, v23 offset1:1
	ds_write2_b32 v103, v24, v25 offset1:1
.LBB0_69:
	s_waitcnt vmcnt(10)
	v_pk_mul_f32 v[4:5], v[18:19], v[206:207] op_sel_hi:[1,0]
	v_pk_mul_f32 v[2:3], v[20:21], v[206:207] op_sel_hi:[1,0]
	s_and_b64 vcc, exec, s[2:3]
	ds_write2_b32 v104, v4, v5 offset1:1
	ds_write2_b32 v105, v2, v3 offset1:1
	s_cbranch_vccnz .LBB0_201
	s_waitcnt vmcnt(9)
	v_pk_mul_f32 v[6:7], v[30:31], v[208:209] op_sel_hi:[1,0]
	v_pk_mul_f32 v[4:5], v[32:33], v[208:209] op_sel_hi:[1,0]
	ds_write2_b32 v106, v6, v7 offset1:1
	ds_write2_b32 v107, v4, v5 offset1:1
	s_cbranch_execnz .LBB0_72
.LBB0_71:
	s_waitcnt vmcnt(0)
	v_mov_b32_e32 v210, 1.0
	ds_write2_b32 v106, v30, v31 offset1:1
	ds_write2_b32 v107, v32, v33 offset1:1
.LBB0_72:
	s_waitcnt vmcnt(8)
	v_pk_mul_f32 v[4:5], v[26:27], v[210:211] op_sel_hi:[1,0]
	v_pk_mul_f32 v[2:3], v[28:29], v[210:211] op_sel_hi:[1,0]
	s_and_b64 vcc, exec, s[2:3]
	ds_write2_b32 v108, v4, v5 offset1:1
	ds_write2_b32 v109, v2, v3 offset1:1
	s_cbranch_vccnz .LBB0_202
	s_waitcnt vmcnt(7)
	v_pk_mul_f32 v[6:7], v[38:39], v[212:213] op_sel_hi:[1,0]
	v_pk_mul_f32 v[4:5], v[40:41], v[212:213] op_sel_hi:[1,0]
	ds_write2_b32 v110, v6, v7 offset1:1
	ds_write2_b32 v111, v4, v5 offset1:1
	s_cbranch_execnz .LBB0_75
.LBB0_74:
	s_waitcnt vmcnt(0)
	v_mov_b32_e32 v214, 1.0
	ds_write2_b32 v110, v38, v39 offset1:1
	ds_write2_b32 v111, v40, v41 offset1:1
.LBB0_75:
	s_waitcnt vmcnt(6)
	v_pk_mul_f32 v[4:5], v[34:35], v[214:215] op_sel_hi:[1,0]
	v_pk_mul_f32 v[2:3], v[36:37], v[214:215] op_sel_hi:[1,0]
	s_and_b64 vcc, exec, s[2:3]
	ds_write2_b32 v112, v4, v5 offset1:1
	ds_write2_b32 v113, v2, v3 offset1:1
	s_cbranch_vccnz .LBB0_203
	s_waitcnt vmcnt(5)
	v_pk_mul_f32 v[6:7], v[46:47], v[216:217] op_sel_hi:[1,0]
	v_pk_mul_f32 v[4:5], v[48:49], v[216:217] op_sel_hi:[1,0]
	ds_write2_b32 v114, v6, v7 offset1:1
	ds_write2_b32 v115, v4, v5 offset1:1
	s_cbranch_execnz .LBB0_78
.LBB0_77:
	s_waitcnt vmcnt(0)
	v_mov_b32_e32 v218, 1.0
	ds_write2_b32 v114, v46, v47 offset1:1
	ds_write2_b32 v115, v48, v49 offset1:1
.LBB0_78:
	s_waitcnt vmcnt(4)
	v_pk_mul_f32 v[4:5], v[42:43], v[218:219] op_sel_hi:[1,0]
	v_pk_mul_f32 v[2:3], v[44:45], v[218:219] op_sel_hi:[1,0]
	s_and_b64 vcc, exec, s[2:3]
	ds_write2_b32 v116, v4, v5 offset1:1
	ds_write2_b32 v117, v2, v3 offset1:1
	s_cbranch_vccnz .LBB0_204
	s_waitcnt vmcnt(3)
	v_pk_mul_f32 v[6:7], v[54:55], v[220:221] op_sel_hi:[1,0]
	v_pk_mul_f32 v[4:5], v[56:57], v[220:221] op_sel_hi:[1,0]
	ds_write2_b32 v118, v6, v7 offset1:1
	ds_write2_b32 v119, v4, v5 offset1:1
	s_cbranch_execnz .LBB0_81
.LBB0_80:
	s_waitcnt vmcnt(0)
	v_mov_b32_e32 v222, 1.0
	ds_write2_b32 v118, v54, v55 offset1:1
	ds_write2_b32 v119, v56, v57 offset1:1
.LBB0_81:
	s_waitcnt vmcnt(2)
	v_pk_mul_f32 v[4:5], v[50:51], v[222:223] op_sel_hi:[1,0]
	v_pk_mul_f32 v[2:3], v[52:53], v[222:223] op_sel_hi:[1,0]
	s_and_b64 vcc, exec, s[2:3]
	ds_write2_b32 v120, v4, v5 offset1:1
	ds_write2_b32 v121, v2, v3 offset1:1
	s_cbranch_vccnz .LBB0_205
	s_waitcnt vmcnt(1)
	v_pk_mul_f32 v[6:7], v[62:63], v[224:225] op_sel_hi:[1,0]
	v_pk_mul_f32 v[4:5], v[64:65], v[224:225] op_sel_hi:[1,0]
	ds_write2_b32 v122, v6, v7 offset1:1
	ds_write2_b32 v123, v4, v5 offset1:1
	s_cbranch_execnz .LBB0_84
.LBB0_83:
	s_waitcnt vmcnt(0)
	v_mov_b32_e32 v226, 1.0
	ds_write2_b32 v122, v62, v63 offset1:1
	ds_write2_b32 v123, v64, v65 offset1:1
.LBB0_84:
	s_waitcnt vmcnt(0)
	v_pk_mul_f32 v[4:5], v[58:59], v[226:227] op_sel_hi:[1,0]
	v_pk_mul_f32 v[2:3], v[60:61], v[226:227] op_sel_hi:[1,0]
	ds_write2_b32 v124, v4, v5 offset1:1
	ds_write2_b32 v125, v2, v3 offset1:1
	s_waitcnt lgkmcnt(0)
	ds_read2_b32 v[8:9], v126 offset0:134 offset1:199
	ds_read2_b32 v[12:13], v126 offset0:4 offset1:69
	ds_read2_b32 v[6:7], v88 offset0:130 offset1:195
	ds_read2_b32 v[10:11], v88 offset1:65
	s_and_b32 s12, 0xffff, s12
	s_cmp_gt_u32 s12, 55
	s_cselect_b64 s[10:11], -1, 0
	s_cmp_lt_u32 s12, 56
	v_or_b32_e32 v66, s92, v87
	s_cbranch_scc1 .LBB0_90
	s_cmp_lg_u32 s12, 56
	s_mov_b64 s[2:3], -1
	s_cbranch_scc0 .LBB0_87
	v_add_u32_e32 v2, -16, v66
	s_mov_b64 s[2:3], 0

.LBB0_772:
	s_or_b64 exec, exec, s[8:9]
	v_ashrrev_i32_e32 v73, 31, v72
	v_cndmask_b32_e64 v1, 0, 1, s[0:1]
	v_cmp_ne_u32_e64 s[2:3], 1, v1
	s_andn2_b64 vcc, exec, s[0:1]
	v_lshl_add_u64 v[72:73], v[72:73], 2, s[44:45]
	s_cbranch_vccnz .LBB0_812
	global_load_dword v74, v[72:73], off
	global_load_dword v66, v[72:73], off offset:16
	global_load_dword v200, v[72:73], off offset:32
	global_load_dword v202, v[72:73], off offset:48
	global_load_dword v204, v[72:73], off offset:64
	global_load_dword v206, v[72:73], off offset:80
	global_load_dword v208, v[72:73], off offset:96
	global_load_dword v210, v[72:73], off offset:112
	global_load_dword v212, v[72:73], off offset:128
	global_load_dword v214, v[72:73], off offset:144
	global_load_dword v216, v[72:73], off offset:160
	global_load_dword v218, v[72:73], off offset:176
	global_load_dword v220, v[72:73], off offset:192
	global_load_dword v222, v[72:73], off offset:208
	global_load_dword v224, v[72:73], off offset:224
	global_load_dword v226, v[72:73], off offset:240
	s_waitcnt vmcnt(15)
	v_pk_mul_f32 v[122:123], v[10:11], v[74:75] op_sel_hi:[1,0]
	v_pk_mul_f32 v[74:75], v[12:13], v[74:75] op_sel_hi:[1,0]
	ds_write2_b32 v78, v122, v123 offset1:1
	ds_write2_b32 v78, v74, v75 offset0:2 offset1:3
	s_cbranch_execnz .LBB0_775

.LBB0_775:
	s_waitcnt vmcnt(14)
	v_pk_mul_f32 v[2:3], v[2:3], v[66:67] op_sel_hi:[1,0]
	ds_write2_b32 v88, v2, v3 offset1:1
	v_pk_mul_f32 v[2:3], v[4:5], v[66:67] op_sel_hi:[1,0]
	s_and_b64 vcc, exec, s[2:3]
	ds_write2_b32 v89, v2, v3 offset1:1
	s_cbranch_vccnz .LBB0_813
	s_waitcnt vmcnt(13)
	v_pk_mul_f32 v[10:11], v[18:19], v[200:201] op_sel_hi:[1,0]
	v_pk_mul_f32 v[4:5], v[20:21], v[200:201] op_sel_hi:[1,0]
	ds_write2_b32 v90, v10, v11 offset1:1
	ds_write2_b32 v91, v4, v5 offset1:1
	s_cbranch_execnz .LBB0_778
.LBB0_777:
	s_waitcnt vmcnt(0)
	v_mov_b32_e32 v202, 1.0
	ds_write2_b32 v90, v18, v19 offset1:1
	ds_write2_b32 v91, v20, v21 offset1:1
.LBB0_778:
	s_waitcnt vmcnt(12)
	v_pk_mul_f32 v[4:5], v[6:7], v[202:203] op_sel_hi:[1,0]
	v_pk_mul_f32 v[2:3], v[8:9], v[202:203] op_sel_hi:[1,0]
	s_and_b64 vcc, exec, s[2:3]
	ds_write2_b32 v92, v4, v5 offset1:1
	ds_write2_b32 v93, v2, v3 offset1:1
	s_cbranch_vccnz .LBB0_814
	s_waitcnt vmcnt(11)
	v_pk_mul_f32 v[6:7], v[26:27], v[204:205] op_sel_hi:[1,0]
	v_pk_mul_f32 v[4:5], v[28:29], v[204:205] op_sel_hi:[1,0]
	ds_write2_b32 v94, v6, v7 offset1:1
	ds_write2_b32 v95, v4, v5 offset1:1
	s_cbranch_execnz .LBB0_781
.LBB0_780:
	s_waitcnt vmcnt(0)
	v_mov_b32_e32 v206, 1.0
	ds_write2_b32 v94, v26, v27 offset1:1
	ds_write2_b32 v95, v28, v29 offset1:1
.LBB0_781:
	s_waitcnt vmcnt(10)
	v_pk_mul_f32 v[4:5], v[14:15], v[206:207] op_sel_hi:[1,0]
	v_pk_mul_f32 v[2:3], v[16:17], v[206:207] op_sel_hi:[1,0]
	s_and_b64 vcc, exec, s[2:3]
	ds_write2_b32 v96, v4, v5 offset1:1
	ds_write2_b32 v97, v2, v3 offset1:1
	s_cbranch_vccnz .LBB0_815
	s_waitcnt vmcnt(9)
	v_pk_mul_f32 v[6:7], v[34:35], v[208:209] op_sel_hi:[1,0]
	v_pk_mul_f32 v[4:5], v[36:37], v[208:209] op_sel_hi:[1,0]
	ds_write2_b32 v98, v6, v7 offset1:1
	ds_write2_b32 v99, v4, v5 offset1:1
	s_cbranch_execnz .LBB0_784
.LBB0_783:
	s_waitcnt vmcnt(0)
	v_mov_b32_e32 v210, 1.0
	ds_write2_b32 v98, v34, v35 offset1:1
	ds_write2_b32 v99, v36, v37 offset1:1
.LBB0_784:
	s_waitcnt vmcnt(8)
	v_pk_mul_f32 v[4:5], v[22:23], v[210:211] op_sel_hi:[1,0]
	v_pk_mul_f32 v[2:3], v[24:25], v[210:211] op_sel_hi:[1,0]
	s_and_b64 vcc, exec, s[2:3]
	ds_write2_b32 v100, v4, v5 offset1:1
	ds_write2_b32 v101, v2, v3 offset1:1
	s_cbranch_vccnz .LBB0_816
	s_waitcnt vmcnt(7)
	v_pk_mul_f32 v[6:7], v[42:43], v[212:213] op_sel_hi:[1,0]
	v_pk_mul_f32 v[4:5], v[44:45], v[212:213] op_sel_hi:[1,0]
	ds_write2_b32 v102, v6, v7 offset1:1
	ds_write2_b32 v103, v4, v5 offset1:1
	s_cbranch_execnz .LBB0_787
.LBB0_786:
	s_waitcnt vmcnt(0)
	v_mov_b32_e32 v214, 1.0
	ds_write2_b32 v102, v42, v43 offset1:1
	ds_write2_b32 v103, v44, v45 offset1:1
.LBB0_787:
	s_waitcnt vmcnt(6)
	v_pk_mul_f32 v[4:5], v[30:31], v[214:215] op_sel_hi:[1,0]
	v_pk_mul_f32 v[2:3], v[32:33], v[214:215] op_sel_hi:[1,0]
	s_and_b64 vcc, exec, s[2:3]
	ds_write2_b32 v104, v4, v5 offset1:1
	ds_write2_b32 v105, v2, v3 offset1:1
	s_cbranch_vccnz .LBB0_817
	s_waitcnt vmcnt(5)
	v_pk_mul_f32 v[6:7], v[50:51], v[216:217] op_sel_hi:[1,0]
	v_pk_mul_f32 v[4:5], v[52:53], v[216:217] op_sel_hi:[1,0]
	ds_write2_b32 v106, v6, v7 offset1:1
	ds_write2_b32 v107, v4, v5 offset1:1
	s_cbranch_execnz .LBB0_790
.LBB0_789:
	s_waitcnt vmcnt(0)
	v_mov_b32_e32 v218, 1.0
	ds_write2_b32 v106, v50, v51 offset1:1
	ds_write2_b32 v107, v52, v53 offset1:1
.LBB0_790:
	s_waitcnt vmcnt(4)
	v_pk_mul_f32 v[4:5], v[38:39], v[218:219] op_sel_hi:[1,0]
	v_pk_mul_f32 v[2:3], v[40:41], v[218:219] op_sel_hi:[1,0]
	s_and_b64 vcc, exec, s[2:3]
	ds_write2_b32 v108, v4, v5 offset1:1
	ds_write2_b32 v109, v2, v3 offset1:1
	s_cbranch_vccnz .LBB0_818
	s_waitcnt vmcnt(3)
	v_pk_mul_f32 v[6:7], v[58:59], v[220:221] op_sel_hi:[1,0]
	v_pk_mul_f32 v[4:5], v[60:61], v[220:221] op_sel_hi:[1,0]
	ds_write2_b32 v110, v6, v7 offset1:1
	ds_write2_b32 v111, v4, v5 offset1:1
	s_cbranch_execnz .LBB0_793
.LBB0_792:
	s_waitcnt vmcnt(0)
	v_mov_b32_e32 v222, 1.0
	ds_write2_b32 v110, v58, v59 offset1:1
	ds_write2_b32 v111, v60, v61 offset1:1
.LBB0_793:
	s_waitcnt vmcnt(2)
	v_pk_mul_f32 v[4:5], v[46:47], v[222:223] op_sel_hi:[1,0]
	v_pk_mul_f32 v[2:3], v[48:49], v[222:223] op_sel_hi:[1,0]
	s_and_b64 vcc, exec, s[2:3]
	ds_write2_b32 v112, v4, v5 offset1:1
	ds_write2_b32 v113, v2, v3 offset1:1
	s_cbranch_vccnz .LBB0_819
	s_waitcnt vmcnt(1)
	v_pk_mul_f32 v[6:7], v[62:63], v[224:225] op_sel_hi:[1,0]
	v_pk_mul_f32 v[4:5], v[64:65], v[224:225] op_sel_hi:[1,0]
	ds_write2_b32 v114, v6, v7 offset1:1
	ds_write2_b32 v115, v4, v5 offset1:1
	s_cbranch_execnz .LBB0_796
.LBB0_795:
	s_waitcnt vmcnt(0)
	v_mov_b32_e32 v226, 1.0
	ds_write2_b32 v114, v62, v63 offset1:1
	ds_write2_b32 v115, v64, v65 offset1:1
.LBB0_796:
	s_waitcnt vmcnt(0)
	v_pk_mul_f32 v[4:5], v[54:55], v[226:227] op_sel_hi:[1,0]
	v_pk_mul_f32 v[2:3], v[56:57], v[226:227] op_sel_hi:[1,0]
	ds_write2_b32 v116, v4, v5 offset1:1
	ds_write2_b32 v117, v2, v3 offset1:1
	s_waitcnt lgkmcnt(0)
	s_ashr_i32 s7, s6, 31
	v_add_u32_e32 v4, s4, v79
	v_lshl_add_u64 v[2:3], s[6:7], 1, v[70:71]
	v_cmp_gt_i32_e32 vcc, s22, v4
	s_and_saveexec_b64 s[2:3], vcc
	s_cbranch_execz .LBB0_798
	ds_read2_b32 v[6:7], v118 offset0:4 offset1:69
	ds_read2_b32 v[8:9], v118 offset0:134 offset1:199
	ds_read2_b32 v[14:15], v80 offset1:65
	ds_read2_b32 v[16:17], v80 offset0:130 offset1:195
	v_cmp_gt_i32_e32 vcc, s19, v4
	s_waitcnt lgkmcnt(3)
	v_mov_b32_e32 v12, v7
	v_cndmask_b32_e32 v10, v119, v120, vcc
	s_waitcnt lgkmcnt(2)
	v_mov_b32_e32 v13, v9
	v_mov_b32_e32 v7, v8
	s_waitcnt lgkmcnt(1)
	v_mov_b32_e32 v8, v15
	s_waitcnt lgkmcnt(0)
	v_mov_b32_e32 v9, v17
	v_mov_b32_e32 v15, v16
	v_pk_mul_f32 v[12:13], v[10:11], v[12:13] op_sel_hi:[0,1]
	v_pk_mul_f32 v[6:7], v[10:11], v[6:7] op_sel_hi:[0,1]
	v_pk_mul_f32 v[8:9], v[10:11], v[8:9] op_sel_hi:[0,1]
	v_pk_mul_f32 v[10:11], v[10:11], v[14:15] op_sel_hi:[0,1]
	v_bfe_u32 v1, v10, 16, 1
	v_bfe_u32 v5, v11, 16, 1
	v_add3_u32 v5, v11, v5, s17
	v_add3_u32 v1, v10, v1, s17
	v_bfe_u32 v15, v8, 16, 1
	v_lshrrev_b32_e32 v1, 16, v1
	v_add3_u32 v15, v8, v15, s17
	v_bfe_u32 v14, v9, 16, 1
	v_cvt_pk_bf16_f32 v8, v6, v12
	v_and_or_b32 v6, v15, s18, v1
	v_add_u32_e32 v1, 0xffffea00, v4
	v_cmp_lt_i32_e32 vcc, s16, v4
	v_lshrrev_b32_e32 v5, 16, v5
	v_add3_u32 v14, v9, v14, s17
	v_cndmask_b32_e32 v1, v4, v1, vcc
	v_cvt_pk_bf16_f32 v9, v7, v13
	v_and_or_b32 v7, v14, s18, v5
	v_lshlrev_b32_e32 v5, 1, v1
	v_and_b32_e32 v5, 0xffffff00, v5
	v_cndmask_b32_e32 v10, 0, v121, vcc
	v_and_b32_e32 v1, 0x47, v1
	v_or3_b32 v10, v1, v10, v5
	v_ashrrev_i32_e32 v11, 31, v10
	v_lshlrev_b64 v[10:11], 12, v[10:11]
	v_lshl_add_u64 v[10:11], v[2:3], 0, v[10:11]
	global_store_dwordx4 v[10:11], v[6:9], off
